# M1: byte-phase pin: third K-loop MFMA run moved from 4 mod 8 to 0 mod 8 (two s_nop 0 in load phases 3 and 4)
# baseline (speedup 1.0000x reference)
; #define PG8_STAGE(bufoff, gbase, voff) do { _Pragma("unroll") for (int _i = 0; _i < 2; ++_i) { unsigned _vo = (voff)[_i]; asm volatile("" : "+v"(_vo));   \
;         __builtin_amdgcn_global_load_lds((const unsigned*)((const char*)(gbase) + _vo), (LAS unsigned*)(lds + (bufoff) + ldsw + _i * 8192), 16, 0, 0); } } while (0)
; #define PG8_LDA(dst, b, h) do { _Pragma("unroll") for (int m = 0; m < 4; ++m) _Pragma("unroll") for (int k = 0; k < 2; ++k) dst[m][k] = *(const LAS bf16x8*)(lds + PG8_SA(b, h) + aoff + m * 2048 + k * 1024); } while (0)
; #define PG8_LDB(dst, b, h) do { _Pragma("unroll") for (int n = 0; n < 2; ++n) _Pragma("unroll") for (int k = 0; k < 2; ++k) dst[n][k] = *(const LAS bf16x8*)(lds + PG8_SB(b, h) + boff + n * 2048 + k * 1024); } while (0)
; #define PG8_MMA(ai, bj, At, Bt) do { __builtin_amdgcn_s_setprio(1); _Pragma("unroll") for (int m = 0; m < 4; ++m) _Pragma("unroll") for (int n = 0; n < 2; ++n) _Pragma("unroll") for (int k = 0; k < 2; ++k) \
;         acc[ai][bj][m][n] = __builtin_amdgcn_mfma_f32_16x16x32_bf16(Bt[n][k], At[m][k], acc[ai][bj][m][n], 0, 0, 0); __builtin_amdgcn_s_setprio(0); } while (0)
; #define PG8_WAIT_V(n) asm volatile("s_waitcnt vmcnt(" #n ")" ::: "memory")
; #define PG8_WAIT_L(n) asm volatile("s_waitcnt lgkmcnt(" #n ")" ::: "memory")
; #define PG8_BAR __builtin_amdgcn_s_barrier()
; #define PG8_SCHED __builtin_amdgcn_sched_barrier(0)
; __device__ __forceinline__ void gemm_phase(LAS unsigned char* lds, const Call& C, const int tid, const Args& args) {
;     ...
;             PG8_LDB(B0, 1, 0); PG8_LDB(B1, 1, 1); PG8_SCHED; PG8_LDA(At, 1, 0); PG8_STAGE(PG8_SA(0, 1), a2 + hstepA, voffA);
;             PG8_WAIT_V(8); PG8_WAIT_L(0); PG8_BAR; PG8_MMA(0, 0, At, B0); PG8_MMA(0, 1, At, B1); PG8_BAR; PG8_SCHED;
.Lp7_ph3:
	s_add_i32 s24, 0, 0x18000
	v_add_u32_e32 v80, s24, v245
	s_add_i32 s42, 0, 0x1c000
	ds_read_b128 v[136:139], v80
	ds_read_b128 v[140:143], v80 offset:1024
	ds_read_b128 v[144:147], v80 offset:2048
	ds_read_b128 v[148:151], v80 offset:3072
	v_add_u32_e32 v80, s42, v245
	ds_read_b128 v[152:155], v80
	ds_read_b128 v[156:159], v80 offset:1024
	ds_read_b128 v[160:163], v80 offset:2048
	ds_read_b128 v[164:167], v80 offset:3072
	s_add_u32 s34, s38, s22
	v_mov_b32_e32 v80, v205
	s_mov_b32 m0, s73
	ds_read_b128 v[168:171], v246 offset:32768
	ds_read_b128 v[172:175], v246 offset:33792
	ds_read_b128 v[176:179], v246 offset:34816
	ds_read_b128 v[180:183], v246 offset:35840
	ds_read_b128 v[184:187], v246 offset:36864
	ds_read_b128 v[188:191], v246 offset:37888
	ds_read_b128 v[192:195], v246 offset:38912
	ds_read_b128 v[196:199], v246 offset:39936
	s_addc_u32 s35, s39, 0
	s_nop 0
	global_load_lds_dwordx4 v80, s[34:35]
	v_mov_b32_e32 v80, v243
	s_mov_b32 m0, s4
	s_nop 0
	global_load_lds_dwordx4 v80, s[34:35]
	s_nop 0
	s_waitcnt vmcnt(8)
	s_waitcnt lgkmcnt(0)
	s_barrier
	s_setprio 1
	s_waitcnt lgkmcnt(0)
	v_mfma_f32_16x16x32_bf16 v[132:135], v[136:139], v[168:171], v[132:135]
	v_mfma_f32_16x16x32_bf16 v[128:131], v[144:147], v[168:171], v[128:131]
	v_mfma_f32_16x16x32_bf16 v[124:127], v[136:139], v[176:179], v[124:127]
	v_mfma_f32_16x16x32_bf16 v[120:123], v[144:147], v[176:179], v[120:123]
	v_mfma_f32_16x16x32_bf16 v[108:111], v[136:139], v[184:187], v[108:111]
	v_mfma_f32_16x16x32_bf16 v[104:107], v[144:147], v[184:187], v[104:107]
	v_mfma_f32_16x16x32_bf16 v[90:93], v[136:139], v[192:195], v[92:95]
	v_mfma_f32_16x16x32_bf16 v[86:89], v[144:147], v[192:195], v[86:89]
	v_mfma_f32_16x16x32_bf16 v[132:135], v[140:143], v[172:175], v[132:135]
	v_mfma_f32_16x16x32_bf16 v[128:131], v[148:151], v[172:175], v[128:131]
	v_mfma_f32_16x16x32_bf16 v[124:127], v[140:143], v[180:183], v[124:127]
	v_mfma_f32_16x16x32_bf16 v[120:123], v[148:151], v[180:183], v[120:123]
	v_mfma_f32_16x16x32_bf16 v[108:111], v[140:143], v[188:191], v[108:111]
	v_mfma_f32_16x16x32_bf16 v[104:107], v[148:151], v[188:191], v[104:107]
	v_mfma_f32_16x16x32_bf16 v[92:95], v[140:143], v[196:199], v[90:93]
	v_mfma_f32_16x16x32_bf16 v[88:91], v[148:151], v[196:199], v[86:89]
	s_setprio 0
	s_setprio 1
	v_mfma_f32_16x16x32_bf16 v[116:119], v[152:155], v[168:171], v[116:119]
	v_mfma_f32_16x16x32_bf16 v[112:115], v[160:163], v[168:171], v[112:115]
	v_mfma_f32_16x16x32_bf16 v[100:103], v[152:155], v[176:179], v[100:103]
	v_mfma_f32_16x16x32_bf16 v[96:99], v[160:163], v[176:179], v[96:99]
	v_mfma_f32_16x16x32_bf16 v[76:79], v[152:155], v[184:187], v[76:79]
	v_mfma_f32_16x16x32_bf16 v[72:75], v[160:163], v[184:187], v[72:75]
	v_mfma_f32_16x16x32_bf16 v[68:71], v[152:155], v[192:195], v[68:71]
	v_mfma_f32_16x16x32_bf16 v[60:63], v[160:163], v[192:195], v[60:63]
	v_mfma_f32_16x16x32_bf16 v[116:119], v[156:159], v[172:175], v[116:119]
	v_mfma_f32_16x16x32_bf16 v[112:115], v[164:167], v[172:175], v[112:115]
	v_mfma_f32_16x16x32_bf16 v[100:103], v[156:159], v[180:183], v[100:103]
	v_mfma_f32_16x16x32_bf16 v[96:99], v[164:167], v[180:183], v[96:99]
	v_mfma_f32_16x16x32_bf16 v[76:79], v[156:159], v[188:191], v[76:79]
	v_mfma_f32_16x16x32_bf16 v[72:75], v[164:167], v[188:191], v[72:75]
	v_mfma_f32_16x16x32_bf16 v[68:71], v[156:159], v[196:199], v[68:71]
	v_mfma_f32_16x16x32_bf16 v[60:63], v[164:167], v[196:199], v[60:63]
	s_setprio 0
	s_barrier
; #define PG8_STAGE(bufoff, gbase, voff) do { _Pragma("unroll") for (int _i = 0; _i < 2; ++_i) { unsigned _vo = (voff)[_i]; asm volatile("" : "+v"(_vo));   \
;         __builtin_amdgcn_global_load_lds((const unsigned*)((const char*)(gbase) + _vo), (LAS unsigned*)(lds + (bufoff) + ldsw + _i * 8192), 16, 0, 0); } } while (0)
; #define PG8_LDA(dst, b, h) do { _Pragma("unroll") for (int m = 0; m < 4; ++m) _Pragma("unroll") for (int k = 0; k < 2; ++k) dst[m][k] = *(const LAS bf16x8*)(lds + PG8_SA(b, h) + aoff + m * 2048 + k * 1024); } while (0)
; #define PG8_MMA(ai, bj, At, Bt) do { __builtin_amdgcn_s_setprio(1); _Pragma("unroll") for (int m = 0; m < 4; ++m) _Pragma("unroll") for (int n = 0; n < 2; ++n) _Pragma("unroll") for (int k = 0; k < 2; ++k) \
;         acc[ai][bj][m][n] = __builtin_amdgcn_mfma_f32_16x16x32_bf16(Bt[n][k], At[m][k], acc[ai][bj][m][n], 0, 0, 0); __builtin_amdgcn_s_setprio(0); } while (0)
; #define PG8_WAIT_V(n) asm volatile("s_waitcnt vmcnt(" #n ")" ::: "memory")
; #define PG8_WAIT_L(n) asm volatile("s_waitcnt lgkmcnt(" #n ")" ::: "memory")
; #define PG8_BAR __builtin_amdgcn_s_barrier()
; #define PG8_SCHED __builtin_amdgcn_sched_barrier(0)
; __device__ __forceinline__ void gemm_phase(LAS unsigned char* lds, const Call& C, const int tid, const Args& args) {
;     ...
;             PG8_LDA(At, 1, 1); PG8_STAGE(PG8_SB(1, 0), b3, voffB); PG8_STAGE(PG8_SB(1, 1), b3 + hstepB, voffB); PG8_STAGE(PG8_SA(1, 0), a3, voffA);
;             PG8_WAIT_V(8); PG8_WAIT_L(0); PG8_BAR; PG8_MMA(1, 0, At, B0); PG8_MMA(1, 1, At, B1); PG8_BAR; PG8_SCHED;
;         }
	v_mov_b32_e32 v80, v242
	ds_read_b128 v[168:171], v246 offset:49152
	ds_read_b128 v[172:175], v246 offset:50176
	ds_read_b128 v[176:179], v246 offset:51200
	ds_read_b128 v[180:183], v246 offset:52224
	ds_read_b128 v[184:187], v246 offset:53248
	ds_read_b128 v[188:191], v246 offset:54272
	ds_read_b128 v[192:195], v246 offset:55296
	ds_read_b128 v[196:199], v246 offset:56320
	s_add_i32 s24, s24, s23
	v_lshl_add_u64 v[82:83], s[40:41], 0, v[80:81]
	v_lshl_add_u64 v[82:83], v[82:83], 0, s[18:19]
	s_mov_b32 m0, s24
	v_mov_b32_e32 v80, v244
	global_load_lds_dwordx4 v[82:83], off
	s_add_i32 m0, s24, 0x2000
	v_lshl_add_u64 v[82:83], s[40:41], 0, v[80:81]
	v_lshl_add_u64 v[82:83], v[82:83], 0, s[18:19]
	v_mov_b32_e32 v80, v242
	global_load_lds_dwordx4 v[82:83], off
	s_add_i32 s24, s42, s23
	v_lshl_add_u64 v[82:83], s[0:1], 0, v[80:81]
	v_lshl_add_u64 v[82:83], v[82:83], 0, s[18:19]
	s_mov_b32 m0, s24
	v_mov_b32_e32 v80, v244
	global_load_lds_dwordx4 v[82:83], off
	s_add_i32 m0, s24, 0x2000
	v_lshl_add_u64 v[82:83], s[0:1], 0, v[80:81]
	v_lshl_add_u64 v[82:83], v[82:83], 0, s[18:19]
	v_mov_b32_e32 v80, v205
	global_load_lds_dwordx4 v[82:83], off
	s_mov_b32 m0, s14
	v_lshl_add_u64 v[82:83], s[38:39], 0, v[80:81]
	v_lshl_add_u64 v[82:83], v[82:83], 0, s[18:19]
	v_mov_b32_e32 v80, v243
	global_load_lds_dwordx4 v[82:83], off
	s_mov_b32 m0, s52
	v_lshl_add_u64 v[82:83], s[38:39], 0, v[80:81]
	v_lshl_add_u64 v[82:83], v[82:83], 0, s[18:19]
	global_load_lds_dwordx4 v[82:83], off
	s_nop 0
	s_waitcnt vmcnt(8)
	s_waitcnt lgkmcnt(0)
	s_barrier
	s_setprio 1
	s_waitcnt lgkmcnt(0)
	v_mfma_f32_16x16x32_bf16 v[64:67], v[136:139], v[168:171], v[64:67]
	v_mfma_f32_16x16x32_bf16 v[56:59], v[144:147], v[168:171], v[56:59]
	v_mfma_f32_16x16x32_bf16 v[52:55], v[136:139], v[176:179], v[52:55]
	v_mfma_f32_16x16x32_bf16 v[48:51], v[144:147], v[176:179], v[48:51]
	v_mfma_f32_16x16x32_bf16 v[36:39], v[136:139], v[184:187], v[36:39]
	v_mfma_f32_16x16x32_bf16 v[32:35], v[144:147], v[184:187], v[32:35]
	v_mfma_f32_16x16x32_bf16 v[20:23], v[136:139], v[192:195], v[20:23]
	v_mfma_f32_16x16x32_bf16 v[16:19], v[144:147], v[192:195], v[16:19]
	v_mfma_f32_16x16x32_bf16 v[64:67], v[140:143], v[172:175], v[64:67]
	v_mfma_f32_16x16x32_bf16 v[56:59], v[148:151], v[172:175], v[56:59]
	v_mfma_f32_16x16x32_bf16 v[52:55], v[140:143], v[180:183], v[52:55]
	v_mfma_f32_16x16x32_bf16 v[48:51], v[148:151], v[180:183], v[48:51]
	v_mfma_f32_16x16x32_bf16 v[36:39], v[140:143], v[188:191], v[36:39]
	v_mfma_f32_16x16x32_bf16 v[32:35], v[148:151], v[188:191], v[32:35]
	v_mfma_f32_16x16x32_bf16 v[20:23], v[140:143], v[196:199], v[20:23]
	v_mfma_f32_16x16x32_bf16 v[16:19], v[148:151], v[196:199], v[16:19]
	s_setprio 0
	s_setprio 1
	v_mfma_f32_16x16x32_bf16 v[44:47], v[152:155], v[168:171], v[44:47]
	v_mfma_f32_16x16x32_bf16 v[40:43], v[160:163], v[168:171], v[40:43]
	v_mfma_f32_16x16x32_bf16 v[28:31], v[152:155], v[176:179], v[28:31]
	v_mfma_f32_16x16x32_bf16 v[24:27], v[160:163], v[176:179], v[24:27]
	v_mfma_f32_16x16x32_bf16 v[12:15], v[152:155], v[184:187], v[12:15]
	v_mfma_f32_16x16x32_bf16 v[8:11], v[160:163], v[184:187], v[8:11]
	v_mfma_f32_16x16x32_bf16 v[4:7], v[152:155], v[192:195], v[4:7]
	v_mfma_f32_16x16x32_bf16 v[0:3], v[160:163], v[192:195], v[0:3]
	v_mfma_f32_16x16x32_bf16 v[44:47], v[156:159], v[172:175], v[44:47]
	v_mfma_f32_16x16x32_bf16 v[40:43], v[164:167], v[172:175], v[40:43]
	v_mfma_f32_16x16x32_bf16 v[28:31], v[156:159], v[180:183], v[28:31]
	v_mfma_f32_16x16x32_bf16 v[24:27], v[164:167], v[180:183], v[24:27]
	v_mfma_f32_16x16x32_bf16 v[12:15], v[156:159], v[188:191], v[12:15]
	v_mfma_f32_16x16x32_bf16 v[8:11], v[164:167], v[188:191], v[8:11]
	v_mfma_f32_16x16x32_bf16 v[4:7], v[156:159], v[196:199], v[4:7]
	v_mfma_f32_16x16x32_bf16 v[0:3], v[164:167], v[196:199], v[0:3]
	s_setprio 0
	s_barrier
	s_add_u32 s16, s16, 0x100
	s_addc_u32 s17, s17, 0
	s_cmp_ge_u32 s25, s12
	s_mov_b64 s[0:1], s[8:9]
	s_mov_b32 s24, s25
	s_cbranch_scc0 .LBB0_282
	s_and_b64 vcc, exec, s[80:81]
	s_cbranch_vccz .LBB0_285
